# F5 EpiBranch: all gate loads hoisted to the epilogue top (one round trip)
# baseline (speedup 1.0000x reference)
.LBB0_987:
	v_add_u32_e32 v216, 0x80, v142
	v_mad_i64_i32 v[216:217], s[8:9], v216, s97, v[144:145]
	v_lshl_add_u64 v[216:217], v[216:217], 0, s[24:25]
	global_load_dwordx2 v[222:223], v[216:217], off
	v_mov_b32_e32 v224, 0
	v_mov_b32_e32 v225, 0
	v_mov_b32_e32 v228, 0
	v_mov_b32_e32 v229, 0
	s_and_b64 vcc, exec, s[6:7]
	s_cbranch_vccnz .Lhoist5_0
	global_load_dwordx2 v[224:225], v[216:217], off offset:2048
	global_load_dwordx2 v[228:229], v[216:217], off offset:2176
.Lhoist5_0:
	global_load_dwordx2 v[226:227], v[216:217], off offset:128
	v_add_u32_e32 v216, 0x90, v142
	v_mad_i64_i32 v[216:217], s[8:9], v216, s97, v[144:145]
	v_lshl_add_u64 v[216:217], v[216:217], 0, s[24:25]
	global_load_dwordx2 v[230:231], v[216:217], off
	v_mov_b32_e32 v232, 0
	v_mov_b32_e32 v233, 0
	v_mov_b32_e32 v236, 0
	v_mov_b32_e32 v237, 0
	s_and_b64 vcc, exec, s[6:7]
	s_cbranch_vccnz .Lhoist5_1
	global_load_dwordx2 v[232:233], v[216:217], off offset:2048
	global_load_dwordx2 v[236:237], v[216:217], off offset:2176
.Lhoist5_1:
	global_load_dwordx2 v[234:235], v[216:217], off offset:128
	v_add_u32_e32 v216, 0xa0, v142
	v_mad_i64_i32 v[216:217], s[8:9], v216, s97, v[144:145]
	v_lshl_add_u64 v[216:217], v[216:217], 0, s[24:25]
	global_load_dwordx2 v[238:239], v[216:217], off
	v_mov_b32_e32 v240, 0
	v_mov_b32_e32 v241, 0
	v_mov_b32_e32 v244, 0
	v_mov_b32_e32 v245, 0
	s_and_b64 vcc, exec, s[6:7]
	s_cbranch_vccnz .Lhoist5_2
	global_load_dwordx2 v[240:241], v[216:217], off offset:2048
	global_load_dwordx2 v[244:245], v[216:217], off offset:2176
.Lhoist5_2:
	global_load_dwordx2 v[242:243], v[216:217], off offset:128
	v_add_u32_e32 v216, 0xb0, v142
	v_mad_i64_i32 v[216:217], s[8:9], v216, s97, v[144:145]
	v_lshl_add_u64 v[216:217], v[216:217], 0, s[24:25]
	global_load_dwordx2 v[246:247], v[216:217], off
	v_mov_b32_e32 v248, 0
	v_mov_b32_e32 v249, 0
	v_mov_b32_e32 v252, 0
	v_mov_b32_e32 v253, 0
	s_and_b64 vcc, exec, s[6:7]
	s_cbranch_vccnz .Lhoist5_3
	global_load_dwordx2 v[248:249], v[216:217], off offset:2048
	global_load_dwordx2 v[252:253], v[216:217], off offset:2176
.Lhoist5_3:
	global_load_dwordx2 v[250:251], v[216:217], off offset:128
	s_waitcnt vmcnt(0)
	v_cvt_f32_ubyte1_e32 v195, v190
	v_cvt_f32_ubyte0_e32 v194, v190
	v_cvt_f32_ubyte3_e32 v197, v190
	v_cvt_f32_ubyte2_e32 v196, v190
	v_cvt_f32_ubyte1_e32 v201, v191
	v_cvt_f32_ubyte0_e32 v200, v191
	v_cvt_f32_ubyte3_e32 v203, v191
	v_cvt_f32_ubyte2_e32 v202, v191
	s_mov_b64 s[8:9], -1
	s_and_b64 vcc, exec, s[22:23]
	s_cbranch_vccz .LBB0_989
	v_cvt_f32_ubyte0_e32 v155, v186
	v_cvt_f32_ubyte1_e32 v157, v186
	v_cvt_f32_ubyte2_e32 v170, v186
	v_cvt_f32_ubyte3_e32 v171, v186
	v_cvt_f32_ubyte0_e32 v185, v187
	v_cvt_f32_ubyte1_e32 v190, v187
	v_cvt_f32_ubyte2_e32 v191, v187
	v_cvt_f32_ubyte3_e32 v199, v187
	v_rcp_iflag_f32_e32 v168, v155
	v_rcp_iflag_f32_e32 v169, v157
	v_rcp_iflag_f32_e32 v170, v170
	v_rcp_iflag_f32_e32 v171, v171
	v_rcp_iflag_f32_e32 v186, v185
	v_rcp_iflag_f32_e32 v187, v190
	v_rcp_iflag_f32_e32 v198, v191
	v_rcp_iflag_f32_e32 v199, v199
	v_pk_mul_f32 v[204:205], v[168:169], v[194:195]
	v_pk_mul_f32 v[206:207], v[170:171], v[196:197]
	v_pk_mul_f32 v[190:191], v[186:187], v[200:201]
	v_pk_mul_f32 v[198:199], v[198:199], v[202:203]
	s_mov_b64 s[8:9], 0

.LBB0_1013:
.LBB0_1015:
	v_add_u32_e32 v156, 0x90, v142
.LBB0_1017:
.LBB0_1019:
	v_cvt_f32_ubyte1_e32 v197, v192
	v_cvt_f32_ubyte0_e32 v196, v192
	v_cvt_f32_ubyte3_e32 v199, v192
	v_cvt_f32_ubyte2_e32 v198, v192
	v_cvt_f32_ubyte1_e32 v203, v193
	v_cvt_f32_ubyte0_e32 v202, v193
	v_cvt_f32_ubyte3_e32 v205, v193
	v_cvt_f32_ubyte2_e32 v204, v193
	s_mov_b64 s[26:27], -1
	s_and_b64 vcc, exec, s[22:23]
	s_cbranch_vccz .LBB0_1021
	v_cvt_f32_ubyte0_e32 v143, v188
	v_cvt_f32_ubyte1_e32 v155, v188
	v_cvt_f32_ubyte2_e32 v157, v188
	v_cvt_f32_ubyte3_e32 v171, v188
	v_cvt_f32_ubyte0_e32 v185, v189
	v_cvt_f32_ubyte1_e32 v187, v189
	v_cvt_f32_ubyte2_e32 v192, v189
	v_cvt_f32_ubyte3_e32 v193, v189
	v_rcp_iflag_f32_e32 v168, v143
	v_rcp_iflag_f32_e32 v169, v155
	v_rcp_iflag_f32_e32 v170, v157
	v_rcp_iflag_f32_e32 v171, v171
	v_rcp_iflag_f32_e32 v188, v185
	v_rcp_iflag_f32_e32 v189, v187
	v_rcp_iflag_f32_e32 v200, v192
	v_rcp_iflag_f32_e32 v201, v193
	v_pk_mul_f32 v[206:207], v[168:169], v[196:197]
	v_pk_mul_f32 v[208:209], v[170:171], v[198:199]
	v_pk_mul_f32 v[192:193], v[188:189], v[202:203]
	v_pk_mul_f32 v[200:201], v[200:201], v[204:205]
	s_mov_b64 s[26:27], 0

.LBB0_1045:
.LBB0_1047:
	v_add_u32_e32 v146, 0xb0, v142
.LBB0_1049:
.LBB0_1051:
	s_waitcnt vmcnt(7)
	v_cvt_f32_ubyte1_e32 v189, v222
	v_cvt_f32_ubyte0_e32 v188, v222
	v_cvt_f32_ubyte3_e32 v197, v222
	v_cvt_f32_ubyte2_e32 v196, v222
	v_cvt_f32_ubyte1_e32 v199, v223
	v_cvt_f32_ubyte0_e32 v198, v223
	v_cvt_f32_ubyte3_e32 v201, v223
	v_cvt_f32_ubyte2_e32 v200, v223
	s_mov_b64 s[24:25], -1
	s_and_b64 vcc, exec, s[22:23]
	s_cbranch_vccz .LBB0_1053
	v_cvt_f32_ubyte0_e32 v147, v224
	v_cvt_f32_ubyte1_e32 v157, v224
	v_cvt_f32_ubyte2_e32 v170, v224
	v_cvt_f32_ubyte3_e32 v171, v224
	v_cvt_f32_ubyte0_e32 v177, v225
	v_cvt_f32_ubyte1_e32 v187, v225
	v_cvt_f32_ubyte2_e32 v192, v225
	v_cvt_f32_ubyte3_e32 v193, v225
	v_rcp_iflag_f32_e32 v168, v147
	v_rcp_iflag_f32_e32 v169, v157
	v_rcp_iflag_f32_e32 v170, v170
	v_rcp_iflag_f32_e32 v171, v171
	v_rcp_iflag_f32_e32 v190, v177
	v_rcp_iflag_f32_e32 v191, v187
	v_rcp_iflag_f32_e32 v194, v192
	v_rcp_iflag_f32_e32 v195, v193
	v_pk_mul_f32 v[202:203], v[168:169], v[188:189]
	v_pk_mul_f32 v[204:205], v[170:171], v[196:197]
	v_pk_mul_f32 v[192:193], v[190:191], v[198:199]
	v_pk_mul_f32 v[194:195], v[194:195], v[200:201]
	s_mov_b64 s[24:25], 0

.LBB0_1057:
	s_waitcnt vmcnt(6)
	s_nop 0
	v_cvt_f32_ubyte1_e32 v189, v226
	v_cvt_f32_ubyte0_e32 v188, v226
	v_cvt_f32_ubyte3_e32 v191, v226
	v_cvt_f32_ubyte2_e32 v190, v226
	v_cvt_f32_ubyte1_e32 v193, v227
	v_cvt_f32_ubyte0_e32 v192, v227
	v_cvt_f32_ubyte3_e32 v197, v227
	v_cvt_f32_ubyte2_e32 v196, v227
	s_and_b64 vcc, exec, s[6:7]
	s_mov_b64 s[24:25], -1
	s_cbranch_vccnz .LBB0_1059
	v_cvt_f32_ubyte0_e32 v147, v228
	v_cvt_f32_ubyte1_e32 v157, v228
	v_cvt_f32_ubyte2_e32 v170, v228
	v_cvt_f32_ubyte3_e32 v171, v228
	v_cvt_f32_ubyte0_e32 v177, v229
	v_cvt_f32_ubyte1_e32 v182, v229
	v_cvt_f32_ubyte2_e32 v183, v229
	v_cvt_f32_ubyte3_e32 v195, v229
	v_rcp_iflag_f32_e32 v168, v147
	v_rcp_iflag_f32_e32 v169, v157
	v_rcp_iflag_f32_e32 v170, v170
	v_rcp_iflag_f32_e32 v171, v171
	v_rcp_iflag_f32_e32 v178, v177
	v_rcp_iflag_f32_e32 v179, v182
	v_rcp_iflag_f32_e32 v194, v183
	v_rcp_iflag_f32_e32 v195, v195
	v_pk_mul_f32 v[198:199], v[168:169], v[188:189]
	v_pk_mul_f32 v[200:201], v[170:171], v[190:191]
	v_pk_mul_f32 v[182:183], v[178:179], v[192:193]
	v_pk_mul_f32 v[194:195], v[194:195], v[196:197]
	s_mov_b64 s[24:25], 0

.LBB0_1063:
	s_waitcnt vmcnt(5)
	v_cvt_f32_ubyte1_e32 v179, v230
	v_cvt_f32_ubyte0_e32 v178, v230
	v_cvt_f32_ubyte3_e32 v183, v230
	v_cvt_f32_ubyte2_e32 v182, v230
	v_cvt_f32_ubyte1_e32 v189, v231
	v_cvt_f32_ubyte0_e32 v188, v231
	v_cvt_f32_ubyte3_e32 v191, v231
	v_cvt_f32_ubyte2_e32 v190, v231
	s_and_b64 vcc, exec, s[6:7]
	s_mov_b64 s[24:25], -1
	s_cbranch_vccnz .LBB0_1065
	v_cvt_f32_ubyte0_e32 v147, v232
	v_cvt_f32_ubyte1_e32 v157, v232
	v_cvt_f32_ubyte2_e32 v168, v232
	v_cvt_f32_ubyte3_e32 v169, v232
	v_cvt_f32_ubyte0_e32 v170, v233
	v_cvt_f32_ubyte1_e32 v171, v233
	v_cvt_f32_ubyte2_e32 v174, v233
	v_cvt_f32_ubyte3_e32 v175, v233
	v_rcp_iflag_f32_e32 v160, v147
	v_rcp_iflag_f32_e32 v161, v157
	v_rcp_iflag_f32_e32 v168, v168
	v_rcp_iflag_f32_e32 v169, v169
	v_rcp_iflag_f32_e32 v170, v170
	v_rcp_iflag_f32_e32 v171, v171
	v_rcp_iflag_f32_e32 v186, v174
	v_rcp_iflag_f32_e32 v187, v175
	v_pk_mul_f32 v[192:193], v[160:161], v[178:179]
	v_pk_mul_f32 v[194:195], v[168:169], v[182:183]
	v_pk_mul_f32 v[174:175], v[170:171], v[188:189]
	v_pk_mul_f32 v[186:187], v[186:187], v[190:191]
	s_mov_b64 s[24:25], 0

.LBB0_1069:
	s_waitcnt vmcnt(4)
	v_cvt_f32_ubyte1_e32 v161, v234
	v_cvt_f32_ubyte0_e32 v160, v234
	v_cvt_f32_ubyte3_e32 v175, v234
	v_cvt_f32_ubyte2_e32 v174, v234
	v_cvt_f32_ubyte1_e32 v179, v235
	v_cvt_f32_ubyte0_e32 v178, v235
	v_cvt_f32_ubyte3_e32 v187, v235
	v_cvt_f32_ubyte2_e32 v186, v235
	s_and_b64 vcc, exec, s[6:7]
	s_mov_b64 s[24:25], -1
	s_cbranch_vccnz .LBB0_1071
	v_cvt_f32_ubyte0_e32 v147, v236
	v_cvt_f32_ubyte1_e32 v152, v236
	v_cvt_f32_ubyte2_e32 v153, v236
	v_cvt_f32_ubyte3_e32 v168, v236
	v_cvt_f32_ubyte0_e32 v169, v237
	v_cvt_f32_ubyte1_e32 v170, v237
	v_cvt_f32_ubyte2_e32 v171, v237
	v_cvt_f32_ubyte3_e32 v177, v237
	v_rcp_iflag_f32_e32 v148, v147
	v_rcp_iflag_f32_e32 v149, v152
	v_rcp_iflag_f32_e32 v152, v153
	v_rcp_iflag_f32_e32 v153, v168
	v_rcp_iflag_f32_e32 v168, v169
	v_rcp_iflag_f32_e32 v169, v170
	v_rcp_iflag_f32_e32 v170, v171
	v_rcp_iflag_f32_e32 v171, v177
	v_pk_mul_f32 v[188:189], v[148:149], v[160:161]
	v_pk_mul_f32 v[190:191], v[152:153], v[174:175]
	v_pk_mul_f32 v[152:153], v[168:169], v[178:179]
	v_pk_mul_f32 v[182:183], v[170:171], v[186:187]
	s_mov_b64 s[24:25], 0

.LBB0_1075:
	s_waitcnt vmcnt(3)
	v_cvt_f32_ubyte1_e32 v149, v238
	v_cvt_f32_ubyte0_e32 v148, v238
	v_cvt_f32_ubyte3_e32 v157, v238
	v_cvt_f32_ubyte2_e32 v156, v238
	v_cvt_f32_ubyte1_e32 v175, v239
	v_cvt_f32_ubyte0_e32 v174, v239
	v_cvt_f32_ubyte3_e32 v179, v239
	v_cvt_f32_ubyte2_e32 v178, v239
	s_mov_b64 s[24:25], -1
	s_and_b64 vcc, exec, s[22:23]
	s_cbranch_vccz .LBB0_1077
	v_cvt_f32_ubyte0_e32 v147, v240
	v_cvt_f32_ubyte1_e32 v153, v240
	v_cvt_f32_ubyte2_e32 v160, v240
	v_cvt_f32_ubyte3_e32 v161, v240
	v_cvt_f32_ubyte0_e32 v168, v241
	v_cvt_f32_ubyte1_e32 v169, v241
	v_cvt_f32_ubyte2_e32 v170, v241
	v_cvt_f32_ubyte3_e32 v171, v241
	v_rcp_iflag_f32_e32 v152, v147
	v_rcp_iflag_f32_e32 v153, v153
	v_rcp_iflag_f32_e32 v160, v160
	v_rcp_iflag_f32_e32 v161, v161
	v_rcp_iflag_f32_e32 v168, v168
	v_rcp_iflag_f32_e32 v169, v169
	v_rcp_iflag_f32_e32 v170, v170
	v_rcp_iflag_f32_e32 v171, v171
	v_pk_mul_f32 v[182:183], v[152:153], v[148:149]
	v_pk_mul_f32 v[184:185], v[160:161], v[156:157]
	v_pk_mul_f32 v[152:153], v[168:169], v[174:175]
	v_pk_mul_f32 v[160:161], v[170:171], v[178:179]
	s_mov_b64 s[24:25], 0

.LBB0_1081:
	s_waitcnt vmcnt(2)
	v_cvt_f32_ubyte1_e32 v153, v242
	v_cvt_f32_ubyte0_e32 v152, v242
	v_cvt_f32_ubyte3_e32 v157, v242
	v_cvt_f32_ubyte2_e32 v156, v242
	v_cvt_f32_ubyte1_e32 v175, v243
	v_cvt_f32_ubyte0_e32 v174, v243
	v_cvt_f32_ubyte3_e32 v177, v243
	v_cvt_f32_ubyte2_e32 v176, v243
	s_and_b64 vcc, exec, s[6:7]
	s_mov_b64 s[22:23], -1
	s_cbranch_vccnz .LBB0_1083
	v_cvt_f32_ubyte0_e32 v147, v244
	v_cvt_f32_ubyte1_e32 v160, v244
	v_cvt_f32_ubyte2_e32 v161, v244
	v_cvt_f32_ubyte3_e32 v168, v244
	v_cvt_f32_ubyte0_e32 v169, v245
	v_cvt_f32_ubyte1_e32 v170, v245
	v_cvt_f32_ubyte2_e32 v171, v245
	v_cvt_f32_ubyte3_e32 v172, v245
	v_rcp_iflag_f32_e32 v158, v147
	v_rcp_iflag_f32_e32 v159, v160
	v_rcp_iflag_f32_e32 v160, v161
	v_rcp_iflag_f32_e32 v161, v168
	v_rcp_iflag_f32_e32 v168, v169
	v_rcp_iflag_f32_e32 v169, v170
	v_rcp_iflag_f32_e32 v170, v171
	v_rcp_iflag_f32_e32 v171, v172
	v_pk_mul_f32 v[178:179], v[158:159], v[152:153]
	v_pk_mul_f32 v[180:181], v[160:161], v[156:157]
	v_pk_mul_f32 v[160:161], v[168:169], v[174:175]
	v_pk_mul_f32 v[172:173], v[170:171], v[176:177]
	s_mov_b64 s[22:23], 0

.LBB0_1087:
	s_waitcnt vmcnt(1)
	v_cvt_f32_ubyte1_e32 v149, v246
	v_cvt_f32_ubyte0_e32 v148, v246
	v_cvt_f32_ubyte3_e32 v157, v246
	v_cvt_f32_ubyte2_e32 v156, v246
	v_cvt_f32_ubyte1_e32 v159, v247
	v_cvt_f32_ubyte0_e32 v158, v247
	v_cvt_f32_ubyte3_e32 v161, v247
	v_cvt_f32_ubyte2_e32 v160, v247
	s_and_b64 vcc, exec, s[6:7]
	s_mov_b64 s[22:23], -1
	s_cbranch_vccnz .LBB0_1089
	v_cvt_f32_ubyte0_e32 v147, v248
	v_cvt_f32_ubyte1_e32 v152, v248
	v_cvt_f32_ubyte2_e32 v153, v248
	v_cvt_f32_ubyte3_e32 v154, v248
	v_cvt_f32_ubyte0_e32 v155, v249
	v_cvt_f32_ubyte1_e32 v168, v249
	v_cvt_f32_ubyte2_e32 v169, v249
	v_cvt_f32_ubyte3_e32 v170, v249
	v_rcp_iflag_f32_e32 v150, v147
	v_rcp_iflag_f32_e32 v151, v152
	v_rcp_iflag_f32_e32 v152, v153
	v_rcp_iflag_f32_e32 v153, v154
	v_rcp_iflag_f32_e32 v154, v155
	v_rcp_iflag_f32_e32 v155, v168
	v_rcp_iflag_f32_e32 v168, v169
	v_rcp_iflag_f32_e32 v169, v170
	v_pk_mul_f32 v[172:173], v[150:151], v[148:149]
	v_pk_mul_f32 v[174:175], v[152:153], v[156:157]
	v_pk_mul_f32 v[152:153], v[154:155], v[158:159]
	v_pk_mul_f32 v[154:155], v[168:169], v[160:161]
	s_mov_b64 s[22:23], 0

.LBB0_1093:
	s_waitcnt vmcnt(0)
	s_nop 0
	v_cvt_f32_ubyte1_e32 v147, v250
	v_cvt_f32_ubyte0_e32 v146, v250
	v_cvt_f32_ubyte3_e32 v149, v250
	v_cvt_f32_ubyte2_e32 v148, v250
	v_cvt_f32_ubyte1_e32 v151, v251
	v_cvt_f32_ubyte0_e32 v150, v251
	v_cvt_f32_ubyte3_e32 v155, v251
	v_cvt_f32_ubyte2_e32 v154, v251
	s_and_b64 vcc, exec, s[6:7]
	s_mov_b64 s[6:7], -1
	s_cbranch_vccnz .LBB0_1095
	v_cvt_f32_ubyte0_e32 v144, v252
	v_cvt_f32_ubyte1_e32 v145, v252
	v_cvt_f32_ubyte2_e32 v152, v252
	v_cvt_f32_ubyte3_e32 v153, v252
	v_cvt_f32_ubyte0_e32 v156, v253
	v_cvt_f32_ubyte1_e32 v157, v253
	v_cvt_f32_ubyte2_e32 v158, v253
	v_cvt_f32_ubyte3_e32 v159, v253
	v_rcp_iflag_f32_e32 v142, v144
	v_rcp_iflag_f32_e32 v143, v145
	v_rcp_iflag_f32_e32 v144, v152
	v_rcp_iflag_f32_e32 v145, v153
	v_rcp_iflag_f32_e32 v152, v156
	v_rcp_iflag_f32_e32 v153, v157
	v_rcp_iflag_f32_e32 v160, v158
	v_rcp_iflag_f32_e32 v161, v159
	v_pk_mul_f32 v[156:157], v[142:143], v[146:147]
	v_pk_mul_f32 v[158:159], v[144:145], v[148:149]
	v_pk_mul_f32 v[144:145], v[152:153], v[150:151]
	v_pk_mul_f32 v[152:153], v[160:161], v[154:155]
	s_mov_b64 s[6:7], 0
